# outproj epilogue: second half's residual loads issued during the first half (fly across the inter-half barriers)
# baseline (speedup 1.0000x reference)
; template <class Epi>
; DI void gemm256(const bf16_t* __restrict__ A, int lda, const bf16_t* __restrict__ Bt, int ldb, int K, char* lds, Epi epi) {
;     ...
;   float* ct = (float*)lds;
; #pragma unroll
;   for (int ai = 0; ai < 2; ++ai) {
;     __syncthreads();
; #pragma unroll
;     for (int bj = 0; bj < 2; ++bj)
; #pragma unroll
;       for (int m = 0; m < 4; ++m)
; #pragma unroll
;         for (int n = 0; n < 2; ++n)
; #pragma unroll
;           for (int j = 0; j < 4; ++j) ct[(wr * 64 + m * 16 + fq * 4 + j) * 260 + bj * 128 + wc * 32 + n * 16 + fr] = acc[ai][bj][m][n][j];
;     __syncthreads();
; #pragma unroll 2
;     for (int it = 0; it < 16; ++it) {
;       const int idx = it * NTHR + tid; const int row = idx >> 6, c4 = (idx & 63) * 4;
;       f32x4 v = *(const f32x4*)(ct + row * 260 + c4);
;       epi(ai * 128 + row, c4, v);
;     }
; DI void phase_outproj(KP p, int l, char* lds) {
;     ...
;       gemm256(Y + (size_t)m0 * 1024, 1024, wo + (size_t)n0 * 1024, 1024, 1024, lds, [&](int m, int n, f32x4 v) {
;         const size_t o = (size_t)m * 1024 + n0 + n;
;         f32x4 xv = __builtin_nontemporal_load((const f32x4*)(src + o)), g = *(const f32x4*)(gt + n0 + n);
;         f32x4 r = {xv[0] + g[0] * v[0], xv[1] + g[1] * v[1], xv[2] + g[2] * v[2], xv[3] + g[3] * v[3]};
;         __builtin_nontemporal_store(r, (f32x4*)(dst + o)); });
.LBB0_349:
	s_or_b64 exec, exec, s[18:19]
	v_lshlrev_b32_e32 v0, 6, v141
	v_lshl_or_b32 v131, v144, 2, v0
	v_lshl_add_u32 v132, v142, 7, 0
	v_lshlrev_b32_e32 v133, 2, v145
	v_mul_lo_u32 v131, v131, s9
	v_add3_u32 v131, v132, v133, v131
	s_waitcnt vmcnt(0)
	s_barrier
	ds_write2_b32 v131, v114, v126 offset1:16
	v_add_u32_e32 v114, 0x400, v131
	ds_write2_b32 v114, v115, v127 offset0:4 offset1:20
	v_add_u32_e32 v115, 0x800, v131
	ds_write2_b32 v115, v116, v128 offset0:8 offset1:24
	v_add_u32_e32 v116, 0xc00, v131
	s_mov_b32 s5, s3
	ds_write2_b32 v116, v117, v129 offset0:12 offset1:28
	v_add_u32_e32 v117, 0x4000, v131
	s_lshl_b32 s2, s50, 20
	s_lshl_b64 s[18:19], s[4:5], 23
	ds_write2_b32 v117, v82, v94 offset0:64 offset1:80
	v_add_u32_e32 v82, 0x4400, v131
	s_or_b32 s2, s18, s2
	ds_write2_b32 v82, v83, v95 offset0:68 offset1:84
	v_add_u32_e32 v83, 0x4800, v131
	s_add_u32 s48, s44, s2
	ds_write2_b32 v83, v84, v96 offset0:72 offset1:88
	v_add_u32_e32 v84, 0x4c00, v131
	s_addc_u32 s49, s45, s19
	ds_write2_b32 v84, v85, v97 offset0:76 offset1:92
	v_add_u32_e32 v85, 0x8000, v131
	s_add_u32 s50, s46, s2
	ds_write2_b32 v85, v74, v78 offset0:128 offset1:144
	v_add_u32_e32 v74, 0x8400, v131
	s_addc_u32 s51, s47, s19
	s_mul_hi_u32 s2, s4, 0x3000
	s_mulk_i32 s4, 0x3000
	ds_write2_b32 v74, v75, v79 offset0:132 offset1:148
	v_add_u32_e32 v75, 0x8800, v131
	s_add_u32 s4, s54, s4
	ds_write2_b32 v75, v76, v80 offset0:136 offset1:152
	v_add_u32_e32 v76, 0x8c00, v131
	s_addc_u32 s2, s55, s2
	ds_write2_b32 v76, v77, v81 offset0:140 offset1:156
	v_add_u32_e32 v77, 0xc000, v131
	s_lshl_b32 s5, s65, 2
	v_and_b32_e32 v134, 0xfc, v143
	ds_write2_b32 v77, v66, v70 offset0:192 offset1:208
	v_add_u32_e32 v70, 0xc400, v131
	s_add_u32 s4, s4, s5
	v_lshlrev_b32_e32 v0, 2, v134
	ds_write2_b32 v70, v67, v71 offset0:196 offset1:212
	v_add_u32_e32 v71, 0xc800, v131
	s_addc_u32 s5, s2, 0
	ds_write2_b32 v71, v68, v72 offset0:200 offset1:216
	v_add_u32_e32 v72, 0xcc00, v131
	v_lshl_add_u64 v[66:67], s[4:5], 0, v[0:1]
	s_mov_b64 s[4:5], 0x2000
	v_add_u32_e32 v130, 0, v0
	ds_write2_b32 v72, v69, v73 offset0:204 offset1:220
	ds_write2_b32 v131, v98, v118 offset0:128 offset1:144
	ds_write2_b32 v114, v99, v119 offset0:132 offset1:148
	ds_write2_b32 v115, v100, v120 offset0:136 offset1:152
	ds_write2_b32 v116, v101, v121 offset0:140 offset1:156
	ds_write2_b32 v117, v102, v122 offset0:192 offset1:208
	ds_write2_b32 v82, v103, v123 offset0:196 offset1:212
	ds_write2_b32 v83, v104, v124 offset0:200 offset1:216
	ds_write2_b32 v84, v105, v125 offset0:204 offset1:220
	ds_write2_b32 v74, v90, v110 offset1:16
	ds_write2_b32 v75, v91, v111 offset0:4 offset1:20
	ds_write2_b32 v76, v92, v112 offset0:8 offset1:24
	v_add_u32_e32 v69, 0x9000, v131
	v_add_u32_e32 v73, 0xd000, v131
	v_lshl_add_u64 v[66:67], v[66:67], 0, s[4:5]
	v_or_b32_e32 v0, s65, v134
	s_mov_b32 s2, 0
	ds_write2_b32 v69, v93, v113 offset0:12 offset1:28
	ds_write2_b32 v70, v86, v106 offset0:64 offset1:80
	ds_write2_b32 v71, v87, v107 offset0:68 offset1:84
	ds_write2_b32 v72, v88, v108 offset0:72 offset1:88
	ds_write2_b32 v73, v89, v109 offset0:76 offset1:92
	s_waitcnt lgkmcnt(0)
	s_barrier
	v_lshrrev_b32_e32 v142, 6, v140
	v_lshlrev_b32_e32 v68, 2, v0
	v_lshl_or_b32 v141, v142, 12, v68
	v_mad_u32_u24 v142, v142, s9, v130
	v_add_u32_e32 v143, 0x10400, v142
	global_load_dwordx4 v[240:243], v[66:67], off
	s_add_u32 s18, s48, 0x0
	s_addc_u32 s19, s49, 0
	global_load_dwordx4 v[144:147], v141, s[18:19] nt
	s_add_u32 s18, s48, 0x8000
	s_addc_u32 s19, s49, 0
	global_load_dwordx4 v[148:151], v141, s[18:19] nt
	s_add_u32 s18, s48, 0x10000
	s_addc_u32 s19, s49, 0
	global_load_dwordx4 v[152:155], v141, s[18:19] nt
	s_add_u32 s18, s48, 0x18000
	s_addc_u32 s19, s49, 0
	global_load_dwordx4 v[156:159], v141, s[18:19] nt
	s_add_u32 s18, s48, 0x20000
	s_addc_u32 s19, s49, 0
	global_load_dwordx4 v[160:163], v141, s[18:19] nt
	s_add_u32 s18, s48, 0x28000
	s_addc_u32 s19, s49, 0
	global_load_dwordx4 v[164:167], v141, s[18:19] nt
	s_add_u32 s18, s48, 0x30000
	s_addc_u32 s19, s49, 0
	global_load_dwordx4 v[168:171], v141, s[18:19] nt
	s_add_u32 s18, s48, 0x38000
	s_addc_u32 s19, s49, 0
	global_load_dwordx4 v[172:175], v141, s[18:19] nt
	s_add_u32 s18, s48, 0x40000
	s_addc_u32 s19, s49, 0
	global_load_dwordx4 v[176:179], v141, s[18:19] nt
	s_add_u32 s18, s48, 0x48000
	s_addc_u32 s19, s49, 0
	global_load_dwordx4 v[180:183], v141, s[18:19] nt
	s_add_u32 s18, s48, 0x50000
	s_addc_u32 s19, s49, 0
	global_load_dwordx4 v[216:219], v141, s[18:19] nt
	s_add_u32 s18, s48, 0x58000
	s_addc_u32 s19, s49, 0
	global_load_dwordx4 v[220:223], v141, s[18:19] nt
	s_add_u32 s18, s48, 0x60000
	s_addc_u32 s19, s49, 0
	global_load_dwordx4 v[224:227], v141, s[18:19] nt
	s_add_u32 s18, s48, 0x68000
	s_addc_u32 s19, s49, 0
	global_load_dwordx4 v[228:231], v141, s[18:19] nt
	s_add_u32 s18, s48, 0x70000
	s_addc_u32 s19, s49, 0
	global_load_dwordx4 v[232:235], v141, s[18:19] nt
	s_add_u32 s18, s48, 0x78000
	s_addc_u32 s19, s49, 0
	global_load_dwordx4 v[236:239], v141, s[18:19] nt
	ds_read_b128 v[244:247], v142 offset:0
	ds_read_b128 v[248:251], v142 offset:8320
	ds_read_b128 v[132:135], v142 offset:16640
	s_add_u32 s20, s50, 0x0
	s_addc_u32 s21, s51, 0
	ds_read_b128 v[136:139], v142 offset:24960
	s_waitcnt vmcnt(15) lgkmcnt(3)
	v_pk_fma_f32 v[246:247], v[246:247], v[242:243], v[146:147]
	v_pk_fma_f32 v[244:245], v[244:245], v[240:241], v[144:145]
	global_store_dwordx4 v141, v[244:247], s[20:21] nt
	s_add_u32 s18, s48, 0x80000
	s_addc_u32 s19, s49, 0
	global_load_dwordx4 v[144:147], v141, s[18:19] nt
	s_add_u32 s20, s50, 0x8000
	s_addc_u32 s21, s51, 0
	ds_read_b128 v[244:247], v142 offset:33280
	s_waitcnt vmcnt(16) lgkmcnt(3)
; template <class Epi>
; DI void gemm256(const bf16_t* __restrict__ A, int lda, const bf16_t* __restrict__ Bt, int ldb, int K, char* lds, Epi epi) {
;     ...
; #pragma unroll 2
;     for (int it = 0; it < 16; ++it) {
;       const int idx = it * NTHR + tid; const int row = idx >> 6, c4 = (idx & 63) * 4;
;       f32x4 v = *(const f32x4*)(ct + row * 260 + c4);
;       epi(ai * 128 + row, c4, v);
;     }
; DI void phase_outproj(KP p, int l, char* lds) {
;     ...
;       gemm256(Y + (size_t)m0 * 1024, 1024, wo + (size_t)n0 * 1024, 1024, 1024, lds, [&](int m, int n, f32x4 v) {
;         const size_t o = (size_t)m * 1024 + n0 + n;
;         f32x4 xv = __builtin_nontemporal_load((const f32x4*)(src + o)), g = *(const f32x4*)(gt + n0 + n);
;         f32x4 r = {xv[0] + g[0] * v[0], xv[1] + g[1] * v[1], xv[2] + g[2] * v[2], xv[3] + g[3] * v[3]};
;         __builtin_nontemporal_store(r, (f32x4*)(dst + o)); });
	v_pk_fma_f32 v[250:251], v[250:251], v[242:243], v[150:151]
	v_pk_fma_f32 v[248:249], v[248:249], v[240:241], v[148:149]
	global_store_dwordx4 v141, v[248:251], s[20:21] nt
	s_add_u32 s18, s48, 0x88000
	s_addc_u32 s19, s49, 0
	global_load_dwordx4 v[148:151], v141, s[18:19] nt
	s_add_u32 s20, s50, 0x10000
	s_addc_u32 s21, s51, 0
	ds_read_b128 v[248:251], v142 offset:41600
	s_waitcnt vmcnt(17) lgkmcnt(3)
	v_pk_fma_f32 v[134:135], v[134:135], v[242:243], v[154:155]
	v_pk_fma_f32 v[132:133], v[132:133], v[240:241], v[152:153]
	global_store_dwordx4 v141, v[132:135], s[20:21] nt
	s_add_u32 s18, s48, 0x90000
	s_addc_u32 s19, s49, 0
	global_load_dwordx4 v[152:155], v141, s[18:19] nt
	s_add_u32 s20, s50, 0x18000
	s_addc_u32 s21, s51, 0
	ds_read_b128 v[132:135], v142 offset:49920
	s_waitcnt vmcnt(18) lgkmcnt(3)
	v_pk_fma_f32 v[138:139], v[138:139], v[242:243], v[158:159]
	v_pk_fma_f32 v[136:137], v[136:137], v[240:241], v[156:157]
	global_store_dwordx4 v141, v[136:139], s[20:21] nt
	s_add_u32 s18, s48, 0x98000
	s_addc_u32 s19, s49, 0
	global_load_dwordx4 v[156:159], v141, s[18:19] nt
	s_add_u32 s20, s50, 0x20000
	s_addc_u32 s21, s51, 0
	ds_read_b128 v[136:139], v142 offset:58240
	s_waitcnt vmcnt(19) lgkmcnt(3)
	v_pk_fma_f32 v[246:247], v[246:247], v[242:243], v[162:163]
	v_pk_fma_f32 v[244:245], v[244:245], v[240:241], v[160:161]
	global_store_dwordx4 v141, v[244:247], s[20:21] nt
	s_add_u32 s18, s48, 0xa0000
	s_addc_u32 s19, s49, 0
	global_load_dwordx4 v[160:163], v141, s[18:19] nt
	s_add_u32 s20, s50, 0x28000
	s_addc_u32 s21, s51, 0
	ds_read_b128 v[244:247], v143 offset:0
	s_waitcnt vmcnt(20) lgkmcnt(3)
	v_pk_fma_f32 v[250:251], v[250:251], v[242:243], v[166:167]
	v_pk_fma_f32 v[248:249], v[248:249], v[240:241], v[164:165]
	global_store_dwordx4 v141, v[248:251], s[20:21] nt
	s_add_u32 s18, s48, 0xa8000
	s_addc_u32 s19, s49, 0
	global_load_dwordx4 v[164:167], v141, s[18:19] nt
	s_add_u32 s20, s50, 0x30000
	s_addc_u32 s21, s51, 0
	ds_read_b128 v[248:251], v143 offset:8320
	s_waitcnt vmcnt(21) lgkmcnt(3)
	v_pk_fma_f32 v[134:135], v[134:135], v[242:243], v[170:171]
	v_pk_fma_f32 v[132:133], v[132:133], v[240:241], v[168:169]
	global_store_dwordx4 v141, v[132:135], s[20:21] nt
	s_add_u32 s18, s48, 0xb0000
	s_addc_u32 s19, s49, 0
	global_load_dwordx4 v[168:171], v141, s[18:19] nt
	s_add_u32 s20, s50, 0x38000
	s_addc_u32 s21, s51, 0
	ds_read_b128 v[132:135], v143 offset:16640
	s_waitcnt vmcnt(22) lgkmcnt(3)
	v_pk_fma_f32 v[138:139], v[138:139], v[242:243], v[174:175]
	v_pk_fma_f32 v[136:137], v[136:137], v[240:241], v[172:173]
	global_store_dwordx4 v141, v[136:139], s[20:21] nt
	s_add_u32 s18, s48, 0xb8000
	s_addc_u32 s19, s49, 0
	global_load_dwordx4 v[172:175], v141, s[18:19] nt
	s_add_u32 s20, s50, 0x40000
	s_addc_u32 s21, s51, 0
	ds_read_b128 v[136:139], v143 offset:24960
	s_waitcnt vmcnt(23) lgkmcnt(3)
	v_pk_fma_f32 v[246:247], v[246:247], v[242:243], v[178:179]
	v_pk_fma_f32 v[244:245], v[244:245], v[240:241], v[176:177]
	global_store_dwordx4 v141, v[244:247], s[20:21] nt
	s_add_u32 s18, s48, 0xc0000
	s_addc_u32 s19, s49, 0
	global_load_dwordx4 v[176:179], v141, s[18:19] nt
	s_add_u32 s20, s50, 0x48000
	s_addc_u32 s21, s51, 0
	ds_read_b128 v[244:247], v143 offset:33280
	s_waitcnt vmcnt(24) lgkmcnt(3)
	v_pk_fma_f32 v[250:251], v[250:251], v[242:243], v[182:183]
	v_pk_fma_f32 v[248:249], v[248:249], v[240:241], v[180:181]
	global_store_dwordx4 v141, v[248:251], s[20:21] nt
	s_add_u32 s18, s48, 0xc8000
	s_addc_u32 s19, s49, 0
	global_load_dwordx4 v[180:183], v141, s[18:19] nt
	s_add_u32 s20, s50, 0x50000
	s_addc_u32 s21, s51, 0
	ds_read_b128 v[248:251], v143 offset:41600
	s_waitcnt vmcnt(25) lgkmcnt(3)
	v_pk_fma_f32 v[134:135], v[134:135], v[242:243], v[218:219]
	v_pk_fma_f32 v[132:133], v[132:133], v[240:241], v[216:217]
	global_store_dwordx4 v141, v[132:135], s[20:21] nt
	s_add_u32 s18, s48, 0xd0000
	s_addc_u32 s19, s49, 0
	global_load_dwordx4 v[216:219], v141, s[18:19] nt
	s_add_u32 s20, s50, 0x58000
	s_addc_u32 s21, s51, 0
	ds_read_b128 v[132:135], v143 offset:49920
	s_waitcnt vmcnt(26) lgkmcnt(3)
	v_pk_fma_f32 v[138:139], v[138:139], v[242:243], v[222:223]
	v_pk_fma_f32 v[136:137], v[136:137], v[240:241], v[220:221]
	global_store_dwordx4 v141, v[136:139], s[20:21] nt
	s_add_u32 s18, s48, 0xd8000
	s_addc_u32 s19, s49, 0
	global_load_dwordx4 v[220:223], v141, s[18:19] nt
	s_add_u32 s20, s50, 0x60000
	s_addc_u32 s21, s51, 0
	ds_read_b128 v[136:139], v143 offset:58240
	s_waitcnt vmcnt(27) lgkmcnt(3)
	v_pk_fma_f32 v[246:247], v[246:247], v[242:243], v[226:227]
	v_pk_fma_f32 v[244:245], v[244:245], v[240:241], v[224:225]
	global_store_dwordx4 v141, v[244:247], s[20:21] nt
	s_add_u32 s18, s48, 0xe0000
	s_addc_u32 s19, s49, 0
	global_load_dwordx4 v[224:227], v141, s[18:19] nt
	s_add_u32 s20, s50, 0x68000
	s_addc_u32 s21, s51, 0
	s_waitcnt vmcnt(28) lgkmcnt(2)
	v_pk_fma_f32 v[250:251], v[250:251], v[242:243], v[230:231]
	v_pk_fma_f32 v[248:249], v[248:249], v[240:241], v[228:229]
	global_store_dwordx4 v141, v[248:251], s[20:21] nt
	s_add_u32 s18, s48, 0xe8000
	s_addc_u32 s19, s49, 0
	global_load_dwordx4 v[228:231], v141, s[18:19] nt
	s_add_u32 s20, s50, 0x70000
	s_addc_u32 s21, s51, 0
	s_waitcnt vmcnt(29) lgkmcnt(1)
	v_pk_fma_f32 v[134:135], v[134:135], v[242:243], v[234:235]
	v_pk_fma_f32 v[132:133], v[132:133], v[240:241], v[232:233]
	global_store_dwordx4 v141, v[132:135], s[20:21] nt
	s_add_u32 s18, s48, 0xf0000
	s_addc_u32 s19, s49, 0
	global_load_dwordx4 v[232:235], v141, s[18:19] nt
	s_add_u32 s20, s50, 0x78000
	s_addc_u32 s21, s51, 0
	s_waitcnt vmcnt(30) lgkmcnt(0)
	v_pk_fma_f32 v[138:139], v[138:139], v[242:243], v[238:239]
	v_pk_fma_f32 v[136:137], v[136:137], v[240:241], v[236:237]
	global_store_dwordx4 v141, v[136:139], s[20:21] nt
	s_add_u32 s18, s48, 0xf8000
	s_addc_u32 s19, s49, 0
	global_load_dwordx4 v[236:239], v141, s[18:19] nt
	s_mov_b32 s2, 0
	s_barrier
; template <class Epi>
; DI void gemm256(const bf16_t* __restrict__ A, int lda, const bf16_t* __restrict__ Bt, int ldb, int K, char* lds, Epi epi) {
;     ...
;   for (int ai = 0; ai < 2; ++ai) {
;     __syncthreads();
; #pragma unroll
;     for (int bj = 0; bj < 2; ++bj)
; #pragma unroll
;       for (int m = 0; m < 4; ++m)
; #pragma unroll
;         for (int n = 0; n < 2; ++n)
; #pragma unroll
;           for (int j = 0; j < 4; ++j) ct[(wr * 64 + m * 16 + fq * 4 + j) * 260 + bj * 128 + wc * 32 + n * 16 + fr] = acc[ai][bj][m][n][j];
;     __syncthreads();
; #pragma unroll 2
;     for (int it = 0; it < 16; ++it) {
;       const int idx = it * NTHR + tid; const int row = idx >> 6, c4 = (idx & 63) * 4;
;       f32x4 v = *(const f32x4*)(ct + row * 260 + c4);
;       epi(ai * 128 + row, c4, v);
;     }
; DI void phase_outproj(KP p, int l, char* lds) {
;     ...
;   for (int j = lb; j < 64; j += nlb) {
;     {
;       const int mi = j >> 2, nt = j & 3;
;       const int bb = 2 * xcd + (mi >> 3), tt = mi & 7;
;       const int m0 = (bb * 9 + tt) * 256, n0 = nt * 256;
;       const float* src = xl + ((size_t)bb * SEQ + tt * 256) * 1024;
;       float* dst = p->out + ((size_t)bb * SEQ + tt * 256) * 1024;
;       const float* gt = mod + (size_t)bb * 3072 + 2048;
;       gemm256(Y + (size_t)m0 * 1024, 1024, wo + (size_t)n0 * 1024, 1024, 1024, lds, [&](int m, int n, f32x4 v) {
;         const size_t o = (size_t)m * 1024 + n0 + n;
;         f32x4 xv = __builtin_nontemporal_load((const f32x4*)(src + o)), g = *(const f32x4*)(gt + n0 + n);
;         f32x4 r = {xv[0] + g[0] * v[0], xv[1] + g[1] * v[1], xv[2] + g[2] * v[2], xv[3] + g[3] * v[3]};
;         __builtin_nontemporal_store(r, (f32x4*)(dst + o)); });
	ds_write2_b32 v131, v2, v18 offset1:16
	ds_write2_b32 v114, v3, v19 offset0:4 offset1:20
	ds_write2_b32 v115, v4, v20 offset0:8 offset1:24
	ds_write2_b32 v116, v5, v21 offset0:12 offset1:28
	ds_write2_b32 v117, v6, v22 offset0:64 offset1:80
	ds_write2_b32 v82, v7, v23 offset0:68 offset1:84
	ds_write2_b32 v83, v8, v24 offset0:72 offset1:88
	ds_write2_b32 v84, v9, v25 offset0:76 offset1:92
	ds_write2_b32 v85, v10, v26 offset0:128 offset1:144
	ds_write2_b32 v74, v11, v27 offset0:132 offset1:148
	ds_write2_b32 v75, v12, v28 offset0:136 offset1:152
	ds_write2_b32 v76, v13, v29 offset0:140 offset1:156
	ds_write2_b32 v77, v14, v30 offset0:192 offset1:208
	ds_write2_b32 v70, v15, v31 offset0:196 offset1:212
	ds_write2_b32 v71, v16, v32 offset0:200 offset1:216
	ds_write2_b32 v72, v17, v33 offset0:204 offset1:220
	ds_write2_b32 v131, v34, v50 offset0:128 offset1:144
	ds_write2_b32 v114, v35, v51 offset0:132 offset1:148
	ds_write2_b32 v115, v36, v52 offset0:136 offset1:152
	ds_write2_b32 v116, v37, v53 offset0:140 offset1:156
	ds_write2_b32 v117, v38, v54 offset0:192 offset1:208
	ds_write2_b32 v82, v39, v55 offset0:196 offset1:212
	ds_write2_b32 v83, v40, v56 offset0:200 offset1:216
	ds_write2_b32 v84, v41, v57 offset0:204 offset1:220
	ds_write2_b32 v74, v42, v58 offset1:16
	ds_write2_b32 v75, v43, v59 offset0:4 offset1:20
	ds_write2_b32 v76, v44, v60 offset0:8 offset1:24
	ds_write2_b32 v69, v45, v61 offset0:12 offset1:28
	ds_write2_b32 v70, v46, v62 offset0:64 offset1:80
	ds_write2_b32 v71, v47, v63 offset0:68 offset1:84
	ds_write2_b32 v72, v48, v64 offset0:72 offset1:88
	ds_write2_b32 v73, v49, v65 offset0:76 offset1:92
	s_waitcnt lgkmcnt(0)
	s_barrier
	ds_read_b128 v[244:247], v142 offset:0
	ds_read_b128 v[248:251], v142 offset:8320
	ds_read_b128 v[132:135], v142 offset:16640
	s_add_u32 s20, s50, 0x80000
	s_addc_u32 s21, s51, 0
	ds_read_b128 v[136:139], v142 offset:24960
	s_waitcnt vmcnt(30) lgkmcnt(3)
	v_pk_fma_f32 v[246:247], v[246:247], v[242:243], v[146:147]
	v_pk_fma_f32 v[244:245], v[244:245], v[240:241], v[144:145]
	global_store_dwordx4 v141, v[244:247], s[20:21] nt
	s_add_u32 s20, s50, 0x88000
	s_addc_u32 s21, s51, 0
	ds_read_b128 v[244:247], v142 offset:33280
	s_waitcnt vmcnt(29) lgkmcnt(3)
	v_pk_fma_f32 v[250:251], v[250:251], v[242:243], v[150:151]
	v_pk_fma_f32 v[248:249], v[248:249], v[240:241], v[148:149]
	global_store_dwordx4 v141, v[248:251], s[20:21] nt
	s_add_u32 s20, s50, 0x90000
	s_addc_u32 s21, s51, 0
	ds_read_b128 v[248:251], v142 offset:41600
	s_waitcnt vmcnt(28) lgkmcnt(3)
	v_pk_fma_f32 v[134:135], v[134:135], v[242:243], v[154:155]
	v_pk_fma_f32 v[132:133], v[132:133], v[240:241], v[152:153]
	global_store_dwordx4 v141, v[132:135], s[20:21] nt
	s_add_u32 s20, s50, 0x98000
	s_addc_u32 s21, s51, 0
	ds_read_b128 v[132:135], v142 offset:49920
	s_waitcnt vmcnt(27) lgkmcnt(3)
	v_pk_fma_f32 v[138:139], v[138:139], v[242:243], v[158:159]
	v_pk_fma_f32 v[136:137], v[136:137], v[240:241], v[156:157]
	global_store_dwordx4 v141, v[136:139], s[20:21] nt
	s_add_u32 s20, s50, 0xa0000
	s_addc_u32 s21, s51, 0
	ds_read_b128 v[136:139], v142 offset:58240
	s_waitcnt vmcnt(26) lgkmcnt(3)
	v_pk_fma_f32 v[246:247], v[246:247], v[242:243], v[162:163]
	v_pk_fma_f32 v[244:245], v[244:245], v[240:241], v[160:161]
	global_store_dwordx4 v141, v[244:247], s[20:21] nt
	s_add_u32 s20, s50, 0xa8000
	s_addc_u32 s21, s51, 0
	ds_read_b128 v[244:247], v143 offset:0
	s_waitcnt vmcnt(25) lgkmcnt(3)
	v_pk_fma_f32 v[250:251], v[250:251], v[242:243], v[166:167]
	v_pk_fma_f32 v[248:249], v[248:249], v[240:241], v[164:165]
	global_store_dwordx4 v141, v[248:251], s[20:21] nt
	s_add_u32 s20, s50, 0xb0000
	s_addc_u32 s21, s51, 0
	ds_read_b128 v[248:251], v143 offset:8320
	s_waitcnt vmcnt(24) lgkmcnt(3)
	v_pk_fma_f32 v[134:135], v[134:135], v[242:243], v[170:171]
	v_pk_fma_f32 v[132:133], v[132:133], v[240:241], v[168:169]
	global_store_dwordx4 v141, v[132:135], s[20:21] nt
	s_add_u32 s20, s50, 0xb8000
	s_addc_u32 s21, s51, 0
	ds_read_b128 v[132:135], v143 offset:16640
	s_waitcnt vmcnt(23) lgkmcnt(3)
	v_pk_fma_f32 v[138:139], v[138:139], v[242:243], v[174:175]
	v_pk_fma_f32 v[136:137], v[136:137], v[240:241], v[172:173]
	global_store_dwordx4 v141, v[136:139], s[20:21] nt
	s_add_u32 s20, s50, 0xc0000
	s_addc_u32 s21, s51, 0
	ds_read_b128 v[136:139], v143 offset:24960
	s_waitcnt vmcnt(22) lgkmcnt(3)
	v_pk_fma_f32 v[246:247], v[246:247], v[242:243], v[178:179]
	v_pk_fma_f32 v[244:245], v[244:245], v[240:241], v[176:177]
	global_store_dwordx4 v141, v[244:247], s[20:21] nt
	s_add_u32 s20, s50, 0xc8000
	s_addc_u32 s21, s51, 0
	ds_read_b128 v[244:247], v143 offset:33280
	s_waitcnt vmcnt(21) lgkmcnt(3)
	v_pk_fma_f32 v[250:251], v[250:251], v[242:243], v[182:183]
	v_pk_fma_f32 v[248:249], v[248:249], v[240:241], v[180:181]
	global_store_dwordx4 v141, v[248:251], s[20:21] nt
	s_add_u32 s20, s50, 0xd0000
	s_addc_u32 s21, s51, 0
	ds_read_b128 v[248:251], v143 offset:41600
	s_waitcnt vmcnt(20) lgkmcnt(3)
	v_pk_fma_f32 v[134:135], v[134:135], v[242:243], v[218:219]
	v_pk_fma_f32 v[132:133], v[132:133], v[240:241], v[216:217]
	global_store_dwordx4 v141, v[132:135], s[20:21] nt
	s_add_u32 s20, s50, 0xd8000
	s_addc_u32 s21, s51, 0
	ds_read_b128 v[132:135], v143 offset:49920
	s_waitcnt vmcnt(19) lgkmcnt(3)
	v_pk_fma_f32 v[138:139], v[138:139], v[242:243], v[222:223]
	v_pk_fma_f32 v[136:137], v[136:137], v[240:241], v[220:221]
	global_store_dwordx4 v141, v[136:139], s[20:21] nt
	s_add_u32 s20, s50, 0xe0000
	s_addc_u32 s21, s51, 0
	ds_read_b128 v[136:139], v143 offset:58240
	s_waitcnt vmcnt(18) lgkmcnt(3)
	v_pk_fma_f32 v[246:247], v[246:247], v[242:243], v[226:227]
	v_pk_fma_f32 v[244:245], v[244:245], v[240:241], v[224:225]
	global_store_dwordx4 v141, v[244:247], s[20:21] nt
	s_add_u32 s20, s50, 0xe8000
	s_addc_u32 s21, s51, 0
	s_waitcnt vmcnt(17) lgkmcnt(2)
	v_pk_fma_f32 v[250:251], v[250:251], v[242:243], v[230:231]
	v_pk_fma_f32 v[248:249], v[248:249], v[240:241], v[228:229]
	global_store_dwordx4 v141, v[248:251], s[20:21] nt
	s_add_u32 s20, s50, 0xf0000
	s_addc_u32 s21, s51, 0
	s_waitcnt vmcnt(16) lgkmcnt(1)
	v_pk_fma_f32 v[134:135], v[134:135], v[242:243], v[234:235]
	v_pk_fma_f32 v[132:133], v[132:133], v[240:241], v[232:233]
	global_store_dwordx4 v141, v[132:135], s[20:21] nt
	s_add_u32 s20, s50, 0xf8000
	s_addc_u32 s21, s51, 0
	s_waitcnt vmcnt(15) lgkmcnt(0)
	v_pk_fma_f32 v[138:139], v[138:139], v[242:243], v[238:239]
	v_pk_fma_f32 v[136:137], v[136:137], v[240:241], v[236:237]
	global_store_dwordx4 v141, v[136:139], s[20:21] nt
	v_readlane_b32 s2, v254, 45
	s_add_i32 s64, s64, s69
	s_add_i32 s57, s57, s2
	s_cmp_gt_u32 s64, 63
	s_barrier
	s_cbranch_scc0 .LBB0_343
